# MLA compute block at s_setprio 1 (staging half stays at 0)
# baseline (speedup 1.0000x reference)
.LBB0_1483:
	s_add_i32 s53, s53, 1
	s_setprio 1
	ds_read_b128 v[212:215], v165
	ds_read_b128 v[216:219], v165 offset:64
	ds_read_b128 v[220:223], v165 offset:128
	ds_read_b128 v[224:227], v165 offset:3584
	ds_read_b128 v[228:231], v165 offset:3648
	s_waitcnt lgkmcnt(4)
	v_mfma_f32_16x16x32_bf16 v[232:235], v[212:215], v[0:3], 0
	v_mfma_f32_16x16x32_bf16 v[240:243], v[212:215], v[12:15], 0
	ds_read_b128 v[212:215], v165 offset:3712
	s_waitcnt lgkmcnt(4)
	v_mfma_f32_16x16x32_bf16 v[232:235], v[216:219], v[4:7], v[232:235]
	v_mfma_f32_16x16x32_bf16 v[240:243], v[216:219], v[16:19], v[240:243]
	ds_read_b128 v[216:219], v165 offset:7168
	s_waitcnt lgkmcnt(4)
	v_mfma_f32_16x16x32_bf16 v[232:235], v[220:223], v[8:11], v[232:235]
	v_mfma_f32_16x16x32_bf16 v[240:243], v[220:223], v[20:23], v[240:243]
	ds_read_b128 v[220:223], v165 offset:7232
	s_waitcnt lgkmcnt(4)
	v_mfma_f32_16x16x32_bf16 v[236:239], v[224:227], v[0:3], 0
	v_mfma_f32_16x16x32_bf16 v[244:247], v[224:227], v[12:15], 0
	ds_read_b128 v[224:227], v165 offset:7296
	s_waitcnt lgkmcnt(4)
	v_mfma_f32_16x16x32_bf16 v[236:239], v[228:231], v[4:7], v[236:239]
	v_mfma_f32_16x16x32_bf16 v[244:247], v[228:231], v[16:19], v[244:247]
	v_exp_f32_e32 v232, v232
	ds_read_b128 v[228:231], v165 offset:10752
	s_waitcnt lgkmcnt(4)
	v_mfma_f32_16x16x32_bf16 v[236:239], v[212:215], v[8:11], v[236:239]
	v_exp_f32_e32 v233, v233
	v_mfma_f32_16x16x32_bf16 v[244:247], v[212:215], v[20:23], v[244:247]
	v_exp_f32_e32 v234, v234
	ds_read_b128 v[212:215], v165 offset:10816
	s_waitcnt lgkmcnt(4)
	v_mfma_f32_16x16x32_bf16 v[168:171], v[216:219], v[0:3], 0
	v_exp_f32_e32 v235, v235
	v_mfma_f32_16x16x32_bf16 v[176:179], v[216:219], v[12:15], 0
	v_cvt_pk_bf16_f32 v232, v232, v233
	v_cvt_pk_bf16_f32 v233, v234, v235
	ds_read_b128 v[216:219], v165 offset:10880
	s_waitcnt lgkmcnt(4)
	v_mfma_f32_16x16x32_bf16 v[168:171], v[220:223], v[4:7], v[168:171]
	v_exp_f32_e32 v240, v240
	v_mfma_f32_16x16x32_bf16 v[176:179], v[220:223], v[16:19], v[176:179]
	v_exp_f32_e32 v241, v241
	ds_read_b128 v[220:223], v160 offset:28672
	s_waitcnt lgkmcnt(4)
	v_mfma_f32_16x16x32_bf16 v[168:171], v[224:227], v[8:11], v[168:171]
	v_exp_f32_e32 v242, v242
	v_mfma_f32_16x16x32_bf16 v[176:179], v[224:227], v[20:23], v[176:179]
	v_exp_f32_e32 v243, v243
	ds_read_b128 v[224:227], v160 offset:33280
	s_waitcnt lgkmcnt(4)
	v_mfma_f32_16x16x32_bf16 v[172:175], v[228:231], v[0:3], 0
	v_cvt_pk_bf16_f32 v240, v240, v241
	v_cvt_pk_bf16_f32 v241, v242, v243
	v_mfma_f32_16x16x32_bf16 v[108:111], v[228:231], v[12:15], 0
	v_exp_f32_e32 v236, v236
	ds_read_b128 v[228:231], v160 offset:37888
	s_waitcnt lgkmcnt(4)
	v_mfma_f32_16x16x32_bf16 v[172:175], v[212:215], v[4:7], v[172:175]
	v_exp_f32_e32 v237, v237
	v_mfma_f32_16x16x32_bf16 v[108:111], v[212:215], v[16:19], v[108:111]
	v_exp_f32_e32 v238, v238
	ds_read_b128 v[212:215], v160 offset:42496
	s_waitcnt lgkmcnt(4)
	v_mfma_f32_16x16x32_bf16 v[172:175], v[216:219], v[8:11], v[172:175]
	v_exp_f32_e32 v239, v239
	v_mfma_f32_16x16x32_bf16 v[108:111], v[216:219], v[20:23], v[108:111]
	v_cvt_pk_bf16_f32 v234, v236, v237
	v_cvt_pk_bf16_f32 v235, v238, v239
	ds_read_b128 v[216:219], v160 offset:47104
	s_waitcnt lgkmcnt(4)
	v_mfma_f32_16x16x32_bf16 v[84:87], v[220:223], v[232:235], v[84:87]
	v_exp_f32_e32 v244, v244
	v_exp_f32_e32 v245, v245
	v_exp_f32_e32 v246, v246
	v_exp_f32_e32 v247, v247
	v_cvt_pk_bf16_f32 v242, v244, v245
	v_cvt_pk_bf16_f32 v243, v246, v247
	v_exp_f32_e32 v168, v168
	v_exp_f32_e32 v169, v169
	v_mfma_f32_16x16x32_bf16 v[68:71], v[220:223], v[240:243], v[68:71]
	v_exp_f32_e32 v170, v170
	ds_read_b128 v[220:223], v165 offset:14336
	s_waitcnt lgkmcnt(4)
	v_mfma_f32_16x16x32_bf16 v[88:91], v[224:227], v[232:235], v[88:91]
	v_exp_f32_e32 v171, v171
	v_mfma_f32_16x16x32_bf16 v[72:75], v[224:227], v[240:243], v[72:75]
	v_cvt_pk_bf16_f32 v168, v168, v169
	v_cvt_pk_bf16_f32 v169, v170, v171
	ds_read_b128 v[224:227], v165 offset:14400
	s_waitcnt lgkmcnt(4)
	v_mfma_f32_16x16x32_bf16 v[92:95], v[228:231], v[232:235], v[92:95]
	v_exp_f32_e32 v176, v176
	v_mfma_f32_16x16x32_bf16 v[76:79], v[228:231], v[240:243], v[76:79]
	v_exp_f32_e32 v177, v177
	ds_read_b128 v[228:231], v165 offset:14464
	s_waitcnt lgkmcnt(4)
	v_mfma_f32_16x16x32_bf16 v[96:99], v[212:215], v[232:235], v[96:99]
	v_exp_f32_e32 v178, v178
	v_mfma_f32_16x16x32_bf16 v[80:83], v[212:215], v[240:243], v[80:83]
	v_exp_f32_e32 v179, v179
	ds_read_b128 v[212:215], v165 offset:17920
	s_waitcnt lgkmcnt(4)
	v_mfma_f32_16x16x32_bf16 v[104:107], v[216:219], v[232:235], v[104:107]
	v_cvt_pk_bf16_f32 v176, v176, v177
	v_cvt_pk_bf16_f32 v177, v178, v179
	v_mfma_f32_16x16x32_bf16 v[100:103], v[216:219], v[240:243], v[100:103]
	v_exp_f32_e32 v172, v172
	ds_read_b128 v[216:219], v165 offset:17984
	s_waitcnt lgkmcnt(4)
	v_mfma_f32_16x16x32_bf16 v[232:235], v[220:223], v[0:3], 0
	v_exp_f32_e32 v173, v173
	v_mfma_f32_16x16x32_bf16 v[240:243], v[220:223], v[12:15], 0
	v_exp_f32_e32 v174, v174
	ds_read_b128 v[220:223], v165 offset:18048
	s_waitcnt lgkmcnt(4)
	v_mfma_f32_16x16x32_bf16 v[232:235], v[224:227], v[4:7], v[232:235]
	v_exp_f32_e32 v175, v175
	v_mfma_f32_16x16x32_bf16 v[240:243], v[224:227], v[16:19], v[240:243]
	v_cvt_pk_bf16_f32 v170, v172, v173
	v_cvt_pk_bf16_f32 v171, v174, v175
	ds_read_b128 v[224:227], v160 offset:28736
	s_waitcnt lgkmcnt(4)
	v_mfma_f32_16x16x32_bf16 v[232:235], v[228:231], v[8:11], v[232:235]
	v_exp_f32_e32 v108, v108
	v_mfma_f32_16x16x32_bf16 v[240:243], v[228:231], v[20:23], v[240:243]
	v_exp_f32_e32 v109, v109
	ds_read_b128 v[228:231], v160 offset:33344
	s_waitcnt lgkmcnt(4)
	v_mfma_f32_16x16x32_bf16 v[236:239], v[212:215], v[0:3], 0
	v_exp_f32_e32 v110, v110
	v_mfma_f32_16x16x32_bf16 v[244:247], v[212:215], v[12:15], 0
	v_exp_f32_e32 v111, v111
	ds_read_b128 v[212:215], v160 offset:37952
	s_waitcnt lgkmcnt(4)
	v_mfma_f32_16x16x32_bf16 v[236:239], v[216:219], v[4:7], v[236:239]
	v_cvt_pk_bf16_f32 v178, v108, v109
	v_cvt_pk_bf16_f32 v179, v110, v111
	v_mfma_f32_16x16x32_bf16 v[244:247], v[216:219], v[16:19], v[244:247]
	v_exp_f32_e32 v232, v232
	ds_read_b128 v[216:219], v160 offset:42560
	s_waitcnt lgkmcnt(4)
	v_mfma_f32_16x16x32_bf16 v[236:239], v[220:223], v[8:11], v[236:239]
	v_exp_f32_e32 v233, v233
	v_mfma_f32_16x16x32_bf16 v[244:247], v[220:223], v[20:23], v[244:247]
	v_exp_f32_e32 v234, v234
	ds_read_b128 v[220:223], v160 offset:47168
	s_waitcnt lgkmcnt(4)
	v_mfma_f32_16x16x32_bf16 v[84:87], v[224:227], v[168:171], v[84:87]
	v_exp_f32_e32 v235, v235
	v_mfma_f32_16x16x32_bf16 v[68:71], v[224:227], v[176:179], v[68:71]
	v_cvt_pk_bf16_f32 v232, v232, v233
	v_cvt_pk_bf16_f32 v233, v234, v235
	ds_read_b128 v[224:227], v165 offset:21504
	s_waitcnt lgkmcnt(4)
	v_mfma_f32_16x16x32_bf16 v[88:91], v[228:231], v[168:171], v[88:91]
	v_exp_f32_e32 v240, v240
	v_mfma_f32_16x16x32_bf16 v[72:75], v[228:231], v[176:179], v[72:75]
	v_exp_f32_e32 v241, v241
	ds_read_b128 v[228:231], v165 offset:21568
	s_waitcnt lgkmcnt(4)
	v_mfma_f32_16x16x32_bf16 v[92:95], v[212:215], v[168:171], v[92:95]
	v_exp_f32_e32 v242, v242
	v_mfma_f32_16x16x32_bf16 v[76:79], v[212:215], v[176:179], v[76:79]
	v_exp_f32_e32 v243, v243
	ds_read_b128 v[212:215], v165 offset:21632
	s_waitcnt lgkmcnt(4)
	v_mfma_f32_16x16x32_bf16 v[96:99], v[216:219], v[168:171], v[96:99]
	v_cvt_pk_bf16_f32 v240, v240, v241
	v_cvt_pk_bf16_f32 v241, v242, v243
	v_mfma_f32_16x16x32_bf16 v[80:83], v[216:219], v[176:179], v[80:83]
	v_exp_f32_e32 v236, v236
	ds_read_b128 v[216:219], v165 offset:25088
	s_waitcnt lgkmcnt(4)
	v_mfma_f32_16x16x32_bf16 v[104:107], v[220:223], v[168:171], v[104:107]
	v_exp_f32_e32 v237, v237
	v_mfma_f32_16x16x32_bf16 v[100:103], v[220:223], v[176:179], v[100:103]
	v_exp_f32_e32 v238, v238
	ds_read_b128 v[220:223], v165 offset:25152
	s_waitcnt lgkmcnt(4)
	v_mfma_f32_16x16x32_bf16 v[168:171], v[224:227], v[0:3], 0
	v_exp_f32_e32 v239, v239
	v_mfma_f32_16x16x32_bf16 v[176:179], v[224:227], v[12:15], 0
	v_cvt_pk_bf16_f32 v234, v236, v237
	v_cvt_pk_bf16_f32 v235, v238, v239
	ds_read_b128 v[224:227], v165 offset:25216
	s_waitcnt lgkmcnt(4)
	v_mfma_f32_16x16x32_bf16 v[168:171], v[228:231], v[4:7], v[168:171]
	v_exp_f32_e32 v244, v244
	v_mfma_f32_16x16x32_bf16 v[176:179], v[228:231], v[16:19], v[176:179]
	v_exp_f32_e32 v245, v245
	ds_read_b128 v[228:231], v160 offset:28800
	s_waitcnt lgkmcnt(4)
	v_mfma_f32_16x16x32_bf16 v[168:171], v[212:215], v[8:11], v[168:171]
	v_exp_f32_e32 v246, v246
	v_mfma_f32_16x16x32_bf16 v[176:179], v[212:215], v[20:23], v[176:179]
	v_exp_f32_e32 v247, v247
	ds_read_b128 v[212:215], v160 offset:33408
	s_waitcnt lgkmcnt(4)
	v_mfma_f32_16x16x32_bf16 v[172:175], v[216:219], v[0:3], 0
	v_cvt_pk_bf16_f32 v242, v244, v245
	v_cvt_pk_bf16_f32 v243, v246, v247
	v_mfma_f32_16x16x32_bf16 v[108:111], v[216:219], v[12:15], 0
	v_exp_f32_e32 v168, v168
	ds_read_b128 v[216:219], v160 offset:38016
	s_waitcnt lgkmcnt(4)
	v_mfma_f32_16x16x32_bf16 v[172:175], v[220:223], v[4:7], v[172:175]
	v_exp_f32_e32 v169, v169
	v_mfma_f32_16x16x32_bf16 v[108:111], v[220:223], v[16:19], v[108:111]
	v_exp_f32_e32 v170, v170
	ds_read_b128 v[220:223], v160 offset:42624
	s_waitcnt lgkmcnt(4)
	v_mfma_f32_16x16x32_bf16 v[172:175], v[224:227], v[8:11], v[172:175]
	v_exp_f32_e32 v171, v171
	v_mfma_f32_16x16x32_bf16 v[108:111], v[224:227], v[20:23], v[108:111]
	v_cvt_pk_bf16_f32 v168, v168, v169
	v_cvt_pk_bf16_f32 v169, v170, v171
	ds_read_b128 v[224:227], v160 offset:47232
	s_waitcnt lgkmcnt(4)
	v_mfma_f32_16x16x32_bf16 v[84:87], v[228:231], v[232:235], v[84:87]
	v_exp_f32_e32 v176, v176
	v_mfma_f32_16x16x32_bf16 v[68:71], v[228:231], v[240:243], v[68:71]
	v_exp_f32_e32 v177, v177
	ds_read_b128 v[228:231], v160 offset:28864
	s_waitcnt lgkmcnt(4)
	v_mfma_f32_16x16x32_bf16 v[88:91], v[212:215], v[232:235], v[88:91]
	v_exp_f32_e32 v178, v178
	v_mfma_f32_16x16x32_bf16 v[72:75], v[212:215], v[240:243], v[72:75]
	v_exp_f32_e32 v179, v179
	ds_read_b128 v[212:215], v160 offset:33472
	s_waitcnt lgkmcnt(4)
	v_mfma_f32_16x16x32_bf16 v[92:95], v[216:219], v[232:235], v[92:95]
	v_cvt_pk_bf16_f32 v176, v176, v177
	v_cvt_pk_bf16_f32 v177, v178, v179
	v_mfma_f32_16x16x32_bf16 v[76:79], v[216:219], v[240:243], v[76:79]
	v_exp_f32_e32 v172, v172
	ds_read_b128 v[216:219], v160 offset:38080
	s_waitcnt lgkmcnt(4)
	v_mfma_f32_16x16x32_bf16 v[96:99], v[220:223], v[232:235], v[96:99]
	v_exp_f32_e32 v173, v173
	v_mfma_f32_16x16x32_bf16 v[80:83], v[220:223], v[240:243], v[80:83]
	v_exp_f32_e32 v174, v174
	ds_read_b128 v[220:223], v160 offset:42688
	s_waitcnt lgkmcnt(4)
	v_mfma_f32_16x16x32_bf16 v[104:107], v[224:227], v[232:235], v[104:107]
	v_exp_f32_e32 v175, v175
	v_mfma_f32_16x16x32_bf16 v[100:103], v[224:227], v[240:243], v[100:103]
	v_cvt_pk_bf16_f32 v170, v172, v173
	v_cvt_pk_bf16_f32 v171, v174, v175
	ds_read_b128 v[224:227], v160 offset:47296
	s_waitcnt lgkmcnt(4)
	v_mfma_f32_16x16x32_bf16 v[84:87], v[228:231], v[168:171], v[84:87]
	v_exp_f32_e32 v108, v108
	s_waitcnt lgkmcnt(3)
	v_mfma_f32_16x16x32_bf16 v[88:91], v[212:215], v[168:171], v[88:91]
	v_exp_f32_e32 v109, v109
	s_waitcnt lgkmcnt(2)
	v_mfma_f32_16x16x32_bf16 v[92:95], v[216:219], v[168:171], v[92:95]
	v_exp_f32_e32 v110, v110
	s_waitcnt lgkmcnt(1)
	v_mfma_f32_16x16x32_bf16 v[96:99], v[220:223], v[168:171], v[96:99]
	v_exp_f32_e32 v111, v111
	s_waitcnt lgkmcnt(0)
	v_mfma_f32_16x16x32_bf16 v[104:107], v[224:227], v[168:171], v[104:107]
	v_cvt_pk_bf16_f32 v178, v108, v109
	v_cvt_pk_bf16_f32 v179, v110, v111
	s_nop 0
	s_nop 0
	v_mfma_f32_16x16x32_bf16 v[68:71], v[228:231], v[176:179], v[68:71]
	v_mfma_f32_16x16x32_bf16 v[72:75], v[212:215], v[176:179], v[72:75]
	v_mfma_f32_16x16x32_bf16 v[76:79], v[216:219], v[176:179], v[76:79]
	v_mfma_f32_16x16x32_bf16 v[80:83], v[220:223], v[176:179], v[80:83]
	v_mfma_f32_16x16x32_bf16 v[100:103], v[224:227], v[176:179], v[100:103]
	s_setprio 0
	s_cmp_eq_u32 s53, 34
	s_cbranch_scc1 .LBB0_1504
